# f20 + diff-attention background-stream loop: V staging wait ladder relaxed 12..9 -> 16..13 (it was also waiting for the bg store acks), V0 drained before loop entry
# speedup vs baseline: 1.0027x; 1.0027x over previous
; __device__ __forceinline__ void bg_load(const BgConv& B, f32x4 (&v)[4], f32x4& gv, int lane) {
;     const int hh = (B.h < BG_NH) ? B.h : BG_NH - 1;
;     const int r = hh >> 1, half = hh & 1, kb = r / 352, nb = r % 352;
;     const float* p = B.src + (size_t)(64 * kb + 4 * half + 8 * (lane & 7)) * (2 * DFF) + 32 * nb + 4 * (lane >> 3);
; #pragma unroll
;     for (int j = 0; j < 4; ++j) v[j] = __builtin_nontemporal_load((const f32x4*)(p + (size_t)j * (2 * DFF)));
;     gv = *(const f32x4*)(B.gain + 64 * kb + 4 * half + 8 * (lane & 7));
; }
;     template <bool BG = false>
;     __device__ __forceinline__ void run(LAS unsigned char* lds, f32x16 (&O)[NCOMP][NBLK], BgConv* bg = nullptr) const {
;     ...
;         if constexpr (BG) {
;             int n = 0; if (bg->h < BG_NH) { n = (BG_NH - 1 - bg->h) / bg->step + 1; const int fit = (ntiles - 1) / 2; n = (n < fit) ? n : fit; }
;             if (n > 0) { bg_load(*bg, bgv, bgg, lane);
; #pragma unroll 1
;                 for (int g = 0; g < n; ++g, t += 2) { body(t, BoolT<true>{}, BoolT<false>{}); body(t + 1, BoolT<true>{}, BoolT<true>{}); } } }
.LBB0_732:
	s_lshl_b32 s87, s81, 2
	v_bfe_u32 v191, v4, 4, 1
	v_and_b32_e32 v192, 3, v4
	v_or_b32_e32 v193, s86, v171
	v_and_b32_e32 v173, 63, v4
	s_sub_i32 s88, s16, s87
	v_bfe_u32 v187, v4, 2, 2
	s_andn2_b64 vcc, exec, s[36:37]
	v_mul_lo_u32 v184, v175, s56
	v_lshlrev_b32_e32 v180, 3, v176
	v_add_u32_e32 v186, s58, v172
	v_mul_lo_u32 v174, v193, s57
	v_lshlrev_b32_e32 v177, 3, v192
	v_lshlrev_b32_e32 v178, 5, v191
	v_add_u32_e32 v188, s59, v172
	v_add_u32_e32 v189, s60, v172
	v_add_u32_e32 v190, s61, v172
	s_cbranch_vccnz .LBB0_739
	s_min_i32 s16, s80, 0x57ff
	s_ashr_i32 s36, s16, 1
	s_mul_hi_i32 s37, s36, 0x2e8ba2e9
	s_lshr_b32 s85, s37, 31
	s_ashr_i32 s37, s37, 6
	s_add_i32 s37, s37, s85
	s_mul_i32 s85, s37, 0x160
	s_lshl_b32 s16, s16, 2
	s_sub_i32 s85, s36, s85
	s_lshl_b32 s36, s37, 6
	s_and_b32 s16, s16, 4
	v_lshlrev_b32_e32 v2, 3, v173
	v_and_b32_e32 v156, 56, v2
	s_or_b32 s37, s36, s16
	v_or_b32_e32 v2, s37, v156
	v_mov_b64_e32 v[8:9], s[50:51]
	v_mad_i64_i32 v[8:9], s[90:91], v2, s54, v[8:9]
	s_lshl_b32 s90, s85, 5
	v_lshrrev_b32_e32 v2, 1, v4
	s_ashr_i32 s91, s90, 31
	v_and_b32_e32 v158, 28, v2
	v_lshl_add_u64 v[8:9], s[90:91], 2, v[8:9]
	v_lshlrev_b32_e32 v2, 2, v158
	v_lshl_add_u64 v[4:5], v[8:9], 0, v[2:3]
	s_ashr_i32 s37, s36, 31
	v_add_co_u32_e32 v8, vcc, s54, v4
	s_lshl_b64 s[36:37], s[36:37], 2
	s_nop 0
	v_addc_co_u32_e32 v9, vcc, 0, v5, vcc
	s_add_u32 s36, s48, s36
	global_load_dwordx4 v[132:135], v[4:5], off nt
	global_load_dwordx4 v[136:139], v[8:9], off nt
	v_add_co_u32_e32 v8, vcc, s43, v4
	s_addc_u32 s37, s49, s37
	s_lshl_b32 s16, s16, 2
	v_addc_co_u32_e32 v9, vcc, 0, v5, vcc
	s_add_u32 s36, s36, s16
	v_add_co_u32_e32 v4, vcc, s55, v4
	s_addc_u32 s37, s37, 0
	v_lshlrev_b32_e32 v2, 2, v156
	v_addc_co_u32_e32 v5, vcc, 0, v5, vcc
	global_load_dwordx4 v[140:143], v[8:9], off nt
	global_load_dwordx4 v[144:147], v[4:5], off nt
	global_load_dwordx4 v[148:151], v2, s[36:37]
	s_lshl_b32 s85, s84, 6
	s_add_i32 s16, s85, s79
	v_lshl_add_u32 v2, v171, 1, s16
	s_lshl_b32 s16, s79, 6
	v_mul_lo_u32 v4, v175, s56
	s_add_i32 s16, s86, s16
	v_add_u32_e32 v8, 0, v4
	v_or_b32_e32 v4, s16, v171
	s_lshl_b32 s36, s72, 4
	v_mul_lo_u32 v4, v4, s57
	v_lshlrev_b32_e32 v5, 3, v176
	s_lshl_b32 s16, s88, 7
	s_lshl_b32 s90, s80, 2
	s_and_b32 s36, s36, 0x600
	v_add3_u32 v9, s58, v4, v5
	v_or_b32_e32 v4, v5, v187
	s_add_u32 s36, s36, s75
	v_mad_u32_u24 v4, v4, s56, 0
	v_lshlrev_b32_e32 v5, 3, v192
	v_lshlrev_b32_e32 v7, 5, v191
	s_addc_u32 s37, 0, s74
	v_add3_u32 v11, v4, v5, v7
	v_mov_b64_e32 v[4:5], s[36:37]
	v_mad_i64_i32 v[4:5], s[36:37], v175, s44, v[4:5]
	v_mov_b32_e32 v7, v3
	v_mul_i32_i24_e32 v185, 0x110, v2
	v_mad_i32_i24 v2, v2, s45, 0
	v_mul_lo_u32 v10, v193, s57
	v_lshl_add_u64 v[4:5], v[4:5], 0, v[6:7]
	v_mov_b32_e32 v181, 0
	v_lshl_add_u64 v[160:161], s[18:19], 0, v[4:5]
	s_lshl_b32 s87, s89, 1
	v_add_u32_e32 v194, v2, v172
	v_add_u32_e32 v195, v8, v179
	v_add_u32_e32 v196, s85, v9
	v_add_u32_e32 v197, v186, v10
	v_add_u32_e32 v198, s16, v11
	v_add_u32_e32 v199, v188, v10
	v_add_u32_e32 v200, v189, v10
	v_add_u32_e32 v201, v190, v10
	v_mov_b32_e32 v4, 0
	v_mov_b32_e32 v5, v181
	v_mov_b32_e32 v6, v181
	v_mov_b32_e32 v7, v181
	v_mov_b32_e32 v8, v181
	v_mov_b32_e32 v9, v181
	v_mov_b32_e32 v10, v181
	v_mov_b32_e32 v11, v181
	v_mov_b32_e32 v12, v181
	v_mov_b32_e32 v13, v181
	v_mov_b32_e32 v14, v181
	v_mov_b32_e32 v15, v181
	v_mov_b32_e32 v16, v181
	v_mov_b32_e32 v17, v181
	v_mov_b32_e32 v18, v181
	v_mov_b32_e32 v19, v181
	v_mov_b32_e32 v20, 0
	v_mov_b32_e32 v21, v181
	v_mov_b32_e32 v22, v181
	v_mov_b32_e32 v23, v181
	v_mov_b32_e32 v24, v181
	v_mov_b32_e32 v25, v181
	v_mov_b32_e32 v26, v181
	v_mov_b32_e32 v27, v181
	v_mov_b32_e32 v28, v181
	v_mov_b32_e32 v29, v181
	v_mov_b32_e32 v30, v181
	v_mov_b32_e32 v31, v181
	v_mov_b32_e32 v32, v181
	v_mov_b32_e32 v33, v181
	v_mov_b32_e32 v34, v181
	v_mov_b32_e32 v35, v181
	v_mov_b32_e32 v36, 0
	v_mov_b32_e32 v37, v181
	v_mov_b32_e32 v38, v181
	v_mov_b32_e32 v39, v181
	v_mov_b32_e32 v40, v181
	v_mov_b32_e32 v41, v181
	v_mov_b32_e32 v42, v181
	v_mov_b32_e32 v43, v181
	v_mov_b32_e32 v44, v181
	v_mov_b32_e32 v45, v181
	v_mov_b32_e32 v46, v181
	v_mov_b32_e32 v47, v181
	v_mov_b32_e32 v48, v181
	v_mov_b32_e32 v49, v181
	v_mov_b32_e32 v50, v181
	v_mov_b32_e32 v51, v181
	v_mov_b32_e32 v52, 0
	v_mov_b32_e32 v53, v181
	v_mov_b32_e32 v54, v181
	v_mov_b32_e32 v55, v181
	v_mov_b32_e32 v56, v181
	v_mov_b32_e32 v57, v181
	v_mov_b32_e32 v58, v181
	v_mov_b32_e32 v59, v181
	v_mov_b32_e32 v60, v181
	v_mov_b32_e32 v61, v181
	v_mov_b32_e32 v62, v181
	v_mov_b32_e32 v63, v181
	v_mov_b32_e32 v64, v181
	v_mov_b32_e32 v65, v181
	v_mov_b32_e32 v66, v181
	v_mov_b32_e32 v67, v181
	s_waitcnt vmcnt(5)
	s_branch .LBB0_735

;     template <bool BG = false>
;     __device__ __forceinline__ void run(LAS unsigned char* lds, f32x16 (&O)[NCOMP][NBLK], BgConv* bg = nullptr) const {
;     ...
;         auto body = [&](const int t, auto moret, auto bgt) {
;             constexpr bool more = decltype(moret)::value, BGI = decltype(bgt)::value;
;             if (more) tile_load(kreg, K + (size_t)(64 * (t + 1)) * ldk, ldk, tid);
;             f32x16 st;
; #pragma unroll
;             for (int i = 0; i < 16; ++i) st[i] = 0.f;
;             if (DH == 128) {
;                 bf16x8 kfa[KS];
; #pragma unroll
;                 for (int s = 0; s < KS; ++s) kfa[s] = *(const LAS bf16x8*)(kbuf + ((32 * kh + r) * NCOMP + compA) * KST + (16 * s + 8 * h) * 2);
;                 asm volatile("" ::: "memory");
;                 tile_store_raw(vreg, vbuf, tid);
; #pragma unroll
;                 for (int s = 0; s < KS; ++s) st = MFMA32(kfa[s], qf[s], st);
;             } else {
;             tile_store_raw(vreg, vbuf, tid);
; #pragma unroll
;             for (int s = 0; s < KS; ++s) { const bf16x8 kf = *(const LAS bf16x8*)(kbuf + ((32 * kh + r) * NCOMP + compA) * KST + (16 * s + 8 * h) * 2); st = MFMA32(kf, qf[s], st);
;                 if ((s & 3) == 3) asm volatile("" ::: "memory"); }
;             }
;             float pe[16];
; #pragma unroll
;             for (int i = 0; i < 16; ++i) { pe[i] = fexp2(st[i] - m2); lsum += pe[i]; }
; #pragma unroll
;             for (int g = 0; g < 4; ++g) { u32x2 w; w.x = pk2(pe[4 * g], pe[4 * g + 1]); w.y = pk2(pe[4 * g + 2], pe[4 * g + 3]);
;                 *(LAS u32x2*)(pbuf + ((compA * NRB + rbA) * 32 + r) * PST + (32 * kh + 8 * g + 4 * h) * 2) = w; }
;             __syncthreads();
;             if (more) tile_load(vreg, V + (size_t)(64 * (t + 1)) * ldv, ldv, tid);
; #pragma unroll
;             for (int s = 0; s < 4; ++s) {
;                 bf16x8 pf[NCOMP];
; #pragma unroll
;                 for (int c = 0; c < NCOMP; ++c) pf[c] = *(const LAS bf16x8*)(pbuf + ((c * NRB + rbB) * 32 + r) * PST + (16 * s + 8 * h) * 2);
; #pragma unroll
;                 for (int b = 0; b < NBLK; ++b) {
;                     const bf16x8 vf = trfrag(vbuf + (16 * s + 8 * h + q4) * VST + (DVW * dvp + 32 * b + 16 * b16 + 4 * p4) * 2, 4 * VST);
; #pragma unroll
;                     for (int c = 0; c < NCOMP; ++c) O[c][b] = MFMA32(pf[c], vf, O[c][b]);
;                 }
.LBB0_735:
	ds_read_b128 v[68:71], v194
	ds_read_b128 v[202:205], v194 offset:32
	v_add_co_u32_e32 v234, vcc, s62, v160
	s_ashr_i32 s36, s80, 1
	s_nop 0
	v_addc_co_u32_e32 v235, vcc, -1, v161, vcc
	s_mul_hi_i32 s16, s36, 0x2e8ba2e9
	s_lshr_b32 s37, s16, 31
	s_waitcnt lgkmcnt(1)
	v_mfma_f32_32x32x16_bf16 v[68:83], v[68:71], v[112:115], 0
	s_ashr_i32 s16, s16, 6
	s_add_i32 s16, s16, s37
	s_mul_i32 s37, s16, 0x160
	s_sub_i32 s93, s36, s37
	s_lshl_b32 s92, s93, 5
	s_mov_b64 s[36:37], -1
	s_cmpk_gt_i32 s93, 0xaf
	s_waitcnt lgkmcnt(0)
	v_mfma_f32_32x32x16_bf16 v[68:83], v[202:205], v[108:111], v[68:83]
	ds_read_b128 v[202:205], v194 offset:64
	s_waitcnt lgkmcnt(0)
	v_mfma_f32_32x32x16_bf16 v[68:83], v[202:205], v[104:107], v[68:83]
	ds_read_b128 v[202:205], v194 offset:96
	s_waitcnt lgkmcnt(0)
	v_mfma_f32_32x32x16_bf16 v[68:83], v[202:205], v[100:103], v[68:83]
	ds_read_b128 v[202:205], v194 offset:128
	s_waitcnt lgkmcnt(0)
	v_mfma_f32_32x32x16_bf16 v[68:83], v[202:205], v[96:99], v[68:83]
	ds_read_b128 v[202:205], v194 offset:160
	ds_read_b128 v[206:209], v194 offset:192
	s_waitcnt lgkmcnt(1)
	v_mfma_f32_32x32x16_bf16 v[68:83], v[202:205], v[92:95], v[68:83]
	ds_read_b128 v[202:205], v194 offset:224
	global_load_dwordx4 v[218:221], v[234:235], off offset:-2432
	global_load_dwordx4 v[222:225], v[234:235], off offset:-2304
	global_load_dwordx4 v[226:229], v[234:235], off offset:-2176
	global_load_dwordx4 v[230:233], v[234:235], off offset:-2048
	s_waitcnt vmcnt(16)
	ds_write_b128 v195, v[128:131] offset:34816
	s_waitcnt vmcnt(15)
	ds_write_b128 v195, v[124:127] offset:34944
	s_waitcnt vmcnt(14)
	ds_write_b128 v195, v[120:123] offset:35072
	s_waitcnt vmcnt(13)
	ds_write_b128 v195, v[116:119] offset:35200
	s_waitcnt lgkmcnt(5)
	v_mfma_f32_32x32x16_bf16 v[68:83], v[206:209], v[88:91], v[68:83]
	s_waitcnt lgkmcnt(4)
	v_mfma_f32_32x32x16_bf16 v[68:83], v[202:205], v[84:87], v[68:83]
	s_nop 11
	v_sub_f32_e32 v2, v68, v170
	v_sub_f32_e32 v68, v69, v170
	v_sub_f32_e32 v69, v70, v170
	v_sub_f32_e32 v70, v71, v170
	v_sub_f32_e32 v71, v72, v170
	v_sub_f32_e32 v72, v73, v170
	v_sub_f32_e32 v73, v74, v170
	v_sub_f32_e32 v74, v75, v170
	v_sub_f32_e32 v75, v76, v170
	v_sub_f32_e32 v76, v77, v170
	v_sub_f32_e32 v77, v78, v170
	v_sub_f32_e32 v78, v79, v170
	v_sub_f32_e32 v79, v80, v170
	v_sub_f32_e32 v80, v81, v170
	v_sub_f32_e32 v81, v82, v170
	v_sub_f32_e32 v82, v83, v170
	v_exp_f32_e32 v2, v2
	v_exp_f32_e32 v202, v68
	v_exp_f32_e32 v203, v69
	v_exp_f32_e32 v204, v70
	v_exp_f32_e32 v205, v71
	v_exp_f32_e32 v206, v72
	v_exp_f32_e32 v207, v73
	v_exp_f32_e32 v208, v74
	v_exp_f32_e32 v209, v75
	v_exp_f32_e32 v210, v76
	v_exp_f32_e32 v211, v77
	v_exp_f32_e32 v212, v78
	v_exp_f32_e32 v213, v79
	v_exp_f32_e32 v214, v80
	v_exp_f32_e32 v215, v81
	v_exp_f32_e32 v216, v82
	v_cvt_pk_bf16_f32 v68, v2, v202
	v_cvt_pk_bf16_f32 v69, v203, v204
	v_cvt_pk_bf16_f32 v70, v205, v206
	v_cvt_pk_bf16_f32 v71, v207, v208
	v_cvt_pk_bf16_f32 v72, v209, v210
	v_cvt_pk_bf16_f32 v73, v211, v212
	v_cvt_pk_bf16_f32 v74, v213, v214
	v_cvt_pk_bf16_f32 v75, v215, v216
	ds_write2_b64 v196, v[68:69], v[70:71] offset1:2
	ds_write2_b64 v196, v[72:73], v[74:75] offset0:4 offset1:6
	s_waitcnt lgkmcnt(0)
	s_barrier
	ds_read_b128 v[68:71], v197
	ds_read_b64_tr_b16 v[72:73], v198 offset:34816
	ds_read_b64_tr_b16 v[74:75], v198 offset:37120
	ds_read_b128 v[76:79], v197 offset:9216
	s_waitcnt lgkmcnt(1)
	v_mfma_f32_32x32x16_bf16 v[52:67], v[68:71], v[72:75], v[52:67]
	s_waitcnt lgkmcnt(0)
	v_mfma_f32_32x32x16_bf16 v[20:35], v[76:79], v[72:75], v[20:35]
	ds_read_b64_tr_b16 v[74:75], v198 offset:37184
	ds_read_b64_tr_b16 v[72:73], v198 offset:34880
	global_load_dwordx4 v[116:119], v[234:235], off offset:-384
	global_load_dwordx4 v[120:123], v[234:235], off offset:-256
	global_load_dwordx4 v[124:127], v[234:235], off offset:-128
	global_load_dwordx4 v[128:131], v[234:235], off
	s_waitcnt lgkmcnt(0)
	v_mfma_f32_32x32x16_bf16 v[36:51], v[68:71], v[72:75], v[36:51]
	v_mfma_f32_32x32x16_bf16 v[4:19], v[76:79], v[72:75], v[4:19]
	ds_read_b128 v[68:71], v199
	ds_read_b64_tr_b16 v[72:73], v198 offset:44032
	ds_read_b64_tr_b16 v[74:75], v198 offset:46336
	ds_read_b128 v[76:79], v199 offset:9216
	s_waitcnt lgkmcnt(1)
	v_mfma_f32_32x32x16_bf16 v[52:67], v[68:71], v[72:75], v[52:67]
	s_waitcnt lgkmcnt(0)
	v_mfma_f32_32x32x16_bf16 v[20:35], v[76:79], v[72:75], v[20:35]
	ds_read_b64_tr_b16 v[74:75], v198 offset:46400
	ds_read_b64_tr_b16 v[72:73], v198 offset:44096
	s_waitcnt vmcnt(7)
	ds_write_b128 v182, v[218:221]
	s_waitcnt vmcnt(6)
	ds_write_b128 v182, v[222:225] offset:128
	s_waitcnt vmcnt(5)
	ds_write_b128 v183, v[226:229]
	s_waitcnt vmcnt(4)
	ds_write_b128 v183, v[230:233] offset:128
	s_waitcnt lgkmcnt(4)
	v_mfma_f32_32x32x16_bf16 v[36:51], v[68:71], v[72:75], v[36:51]
	v_mfma_f32_32x32x16_bf16 v[4:19], v[76:79], v[72:75], v[4:19]
	ds_read_b128 v[68:71], v200
	ds_read_b64_tr_b16 v[72:73], v198 offset:53248
	ds_read_b64_tr_b16 v[74:75], v198 offset:55552
	ds_read_b128 v[76:79], v200 offset:9216
	s_waitcnt lgkmcnt(1)
	v_mfma_f32_32x32x16_bf16 v[52:67], v[68:71], v[72:75], v[52:67]
	s_waitcnt lgkmcnt(0)
	v_mfma_f32_32x32x16_bf16 v[20:35], v[76:79], v[72:75], v[20:35]
	ds_read_b64_tr_b16 v[74:75], v198 offset:55616
	ds_read_b64_tr_b16 v[72:73], v198 offset:53312
	s_waitcnt lgkmcnt(0)
	v_mfma_f32_32x32x16_bf16 v[36:51], v[68:71], v[72:75], v[36:51]
	v_mfma_f32_32x32x16_bf16 v[4:19], v[76:79], v[72:75], v[4:19]
	ds_read_b128 v[68:71], v201
	ds_read_b64_tr_b16 v[72:73], v198 offset:62464
	ds_read_b64_tr_b16 v[74:75], v198 offset:64768
	ds_read_b128 v[76:79], v201 offset:9216
	s_waitcnt lgkmcnt(1)
	v_mfma_f32_32x32x16_bf16 v[52:67], v[68:71], v[72:75], v[52:67]
	s_waitcnt lgkmcnt(0)
	v_mfma_f32_32x32x16_bf16 v[20:35], v[76:79], v[72:75], v[20:35]
	ds_read_b64_tr_b16 v[74:75], v198 offset:64832
	ds_read_b64_tr_b16 v[72:73], v198 offset:62528
	s_waitcnt lgkmcnt(0)
	s_barrier
;     template <bool BG = false>
;     __device__ __forceinline__ void run(LAS unsigned char* lds, f32x16 (&O)[NCOMP][NBLK], BgConv* bg = nullptr) const {
;     ...
;         auto body = [&](const int t, auto moret, auto bgt) {
;             constexpr bool more = decltype(moret)::value, BGI = decltype(bgt)::value;
;             if (more) tile_load(kreg, K + (size_t)(64 * (t + 1)) * ldk, ldk, tid);
;             f32x16 st;
; #pragma unroll
;             for (int i = 0; i < 16; ++i) st[i] = 0.f;
;             if (DH == 128) {
;                 bf16x8 kfa[KS];
; #pragma unroll
;                 for (int s = 0; s < KS; ++s) kfa[s] = *(const LAS bf16x8*)(kbuf + ((32 * kh + r) * NCOMP + compA) * KST + (16 * s + 8 * h) * 2);
;                 asm volatile("" ::: "memory");
;                 tile_store_raw(vreg, vbuf, tid);
; #pragma unroll
;                 for (int s = 0; s < KS; ++s) st = MFMA32(kfa[s], qf[s], st);
;             } else {
;             tile_store_raw(vreg, vbuf, tid);
; #pragma unroll
;             for (int s = 0; s < KS; ++s) { const bf16x8 kf = *(const LAS bf16x8*)(kbuf + ((32 * kh + r) * NCOMP + compA) * KST + (16 * s + 8 * h) * 2); st = MFMA32(kf, qf[s], st);
;                 if ((s & 3) == 3) asm volatile("" ::: "memory"); }
;             }
;             float pe[16];
; #pragma unroll
;             for (int i = 0; i < 16; ++i) { pe[i] = fexp2(st[i] - m2); lsum += pe[i]; }
; #pragma unroll
;             for (int g = 0; g < 4; ++g) { u32x2 w; w.x = pk2(pe[4 * g], pe[4 * g + 1]); w.y = pk2(pe[4 * g + 2], pe[4 * g + 3]);
;                 *(LAS u32x2*)(pbuf + ((compA * NRB + rbA) * 32 + r) * PST + (32 * kh + 8 * g + 4 * h) * 2) = w; }
;             __syncthreads();
;             if (more) tile_load(vreg, V + (size_t)(64 * (t + 1)) * ldv, ldv, tid);
; #pragma unroll
;             for (int s = 0; s < 4; ++s) {
;                 bf16x8 pf[NCOMP];
; #pragma unroll
;                 for (int c = 0; c < NCOMP; ++c) pf[c] = *(const LAS bf16x8*)(pbuf + ((c * NRB + rbB) * 32 + r) * PST + (16 * s + 8 * h) * 2);
; #pragma unroll
;                 for (int b = 0; b < NBLK; ++b) {
;                     const bf16x8 vf = trfrag(vbuf + (16 * s + 8 * h + q4) * VST + (DVW * dvp + 32 * b + 16 * b16 + 4 * p4) * 2, 4 * VST);
; #pragma unroll
;                     for (int c = 0; c < NCOMP; ++c) O[c][b] = MFMA32(pf[c], vf, O[c][b]);
;                 }
	ds_read_b128 v[218:221], v194 offset:32
	v_mfma_f32_32x32x16_bf16 v[36:51], v[68:71], v[72:75], v[36:51]
	ds_read_b128 v[68:71], v194
	v_mfma_f32_32x32x16_bf16 v[4:19], v[76:79], v[72:75], v[4:19]
	s_waitcnt lgkmcnt(0)
	v_mfma_f32_32x32x16_bf16 v[68:83], v[68:71], v[112:115], 0
	v_mfma_f32_32x32x16_bf16 v[68:83], v[218:221], v[108:111], v[68:83]
	ds_read_b128 v[218:221], v194 offset:64
	s_waitcnt lgkmcnt(0)
	v_mfma_f32_32x32x16_bf16 v[68:83], v[218:221], v[104:107], v[68:83]
	ds_read_b128 v[218:221], v194 offset:96
	s_waitcnt lgkmcnt(0)
	v_mfma_f32_32x32x16_bf16 v[68:83], v[218:221], v[100:103], v[68:83]
	ds_read_b128 v[218:221], v194 offset:128
	s_waitcnt lgkmcnt(0)
	v_mfma_f32_32x32x16_bf16 v[68:83], v[218:221], v[96:99], v[68:83]
	ds_read_b128 v[218:221], v194 offset:160
	s_waitcnt lgkmcnt(0)
	v_mfma_f32_32x32x16_bf16 v[68:83], v[218:221], v[92:95], v[68:83]
	ds_read_b128 v[218:221], v194 offset:192
	global_load_dwordx4 v[222:225], v[160:161], off offset:-2432
	global_load_dwordx4 v[226:229], v[160:161], off offset:-2304
	ds_read_b128 v[230:233], v194 offset:224
	s_waitcnt lgkmcnt(1)
	v_mfma_f32_32x32x16_bf16 v[68:83], v[218:221], v[88:91], v[68:83]
	global_load_dwordx4 v[218:221], v[160:161], off offset:-2176
	global_load_dwordx4 v[234:237], v[160:161], off offset:-2048
	s_waitcnt vmcnt(7)
	ds_write_b128 v195, v[116:119] offset:34816
	s_waitcnt vmcnt(6)
	ds_write_b128 v195, v[120:123] offset:34944
	s_waitcnt vmcnt(5)
	ds_write_b128 v195, v[124:127] offset:35072
	s_waitcnt vmcnt(4)
	ds_write_b128 v195, v[128:131] offset:35200
	s_waitcnt lgkmcnt(4)
	v_mfma_f32_32x32x16_bf16 v[68:83], v[230:233], v[84:87], v[68:83]
	s_nop 11
	v_sub_f32_e32 v68, v68, v170
	v_sub_f32_e32 v69, v69, v170
	v_sub_f32_e32 v70, v70, v170
	v_sub_f32_e32 v71, v71, v170
	v_sub_f32_e32 v72, v72, v170
	v_sub_f32_e32 v73, v73, v170
	v_sub_f32_e32 v74, v74, v170
	v_sub_f32_e32 v75, v75, v170
	v_exp_f32_e32 v68, v68
	v_exp_f32_e32 v69, v69
	v_exp_f32_e32 v70, v70
	v_exp_f32_e32 v71, v71
	v_exp_f32_e32 v72, v72
	v_exp_f32_e32 v73, v73
	v_exp_f32_e32 v74, v74
	v_exp_f32_e32 v75, v75
	v_sub_f32_e32 v76, v76, v170
	v_sub_f32_e32 v77, v77, v170
	v_sub_f32_e32 v78, v78, v170
	v_sub_f32_e32 v79, v79, v170
	v_sub_f32_e32 v80, v80, v170
	v_sub_f32_e32 v81, v81, v170
	v_sub_f32_e32 v82, v82, v170
	v_sub_f32_e32 v83, v83, v170
	v_exp_f32_e32 v76, v76
	v_exp_f32_e32 v77, v77
	v_exp_f32_e32 v78, v78
	v_exp_f32_e32 v79, v79
	v_exp_f32_e32 v80, v80
	v_exp_f32_e32 v81, v81
	v_exp_f32_e32 v82, v82
	v_exp_f32_e32 v83, v83
	v_cvt_pk_bf16_f32 v116, v68, v69
	v_cvt_pk_bf16_f32 v117, v70, v71
	v_cvt_pk_bf16_f32 v118, v72, v73
	v_cvt_pk_bf16_f32 v119, v74, v75
	ds_write2_b64 v196, v[116:117], v[118:119] offset1:2
	v_cvt_pk_bf16_f32 v116, v76, v77
	v_cvt_pk_bf16_f32 v117, v78, v79
	v_cvt_pk_bf16_f32 v118, v80, v81
	v_cvt_pk_bf16_f32 v119, v82, v83
	ds_write2_b64 v196, v[116:117], v[118:119] offset0:4 offset1:6
	s_waitcnt lgkmcnt(0)
	s_barrier
	ds_read_b128 v[116:119], v197
	ds_read_b64_tr_b16 v[120:121], v198 offset:34816
	ds_read_b64_tr_b16 v[122:123], v198 offset:37120
	ds_read_b128 v[230:233], v197 offset:9216
	ds_read_b64_tr_b16 v[240:241], v198 offset:37184
	ds_read_b64_tr_b16 v[238:239], v198 offset:34880
	s_waitcnt lgkmcnt(3)
	v_mfma_f32_32x32x16_bf16 v[52:67], v[116:119], v[120:123], v[52:67]
	s_waitcnt lgkmcnt(2)
	v_mfma_f32_32x32x16_bf16 v[20:35], v[230:233], v[120:123], v[20:35]
	s_waitcnt lgkmcnt(0)
	v_mfma_f32_32x32x16_bf16 v[36:51], v[116:119], v[238:241], v[36:51]
	global_load_dwordx4 v[128:131], v[160:161], off offset:-384
	global_load_dwordx4 v[124:127], v[160:161], off offset:-256
	global_load_dwordx4 v[120:123], v[160:161], off offset:-128
	global_load_dwordx4 v[116:119], v[160:161], off
	v_mfma_f32_32x32x16_bf16 v[4:19], v[230:233], v[238:241], v[4:19]
	ds_read_b128 v[230:233], v199
	ds_read_b64_tr_b16 v[238:239], v198 offset:44032
	ds_read_b64_tr_b16 v[240:241], v198 offset:46336
	ds_read_b128 v[242:245], v199 offset:9216
	s_waitcnt lgkmcnt(1)
	v_mfma_f32_32x32x16_bf16 v[52:67], v[230:233], v[238:241], v[52:67]
	s_waitcnt lgkmcnt(0)
	v_mfma_f32_32x32x16_bf16 v[20:35], v[242:245], v[238:241], v[20:35]
	ds_read_b64_tr_b16 v[240:241], v198 offset:46400
	ds_read_b64_tr_b16 v[238:239], v198 offset:44096
	s_waitcnt vmcnt(7)
	ds_write_b128 v182, v[222:225]
	s_waitcnt vmcnt(6)
	ds_write_b128 v182, v[226:229] offset:128
	s_waitcnt vmcnt(5)
	ds_write_b128 v183, v[218:221]
	s_waitcnt vmcnt(4)
	ds_write_b128 v183, v[234:237] offset:128
	ds_read_b128 v[218:221], v200
	ds_read_b64_tr_b16 v[222:223], v198 offset:53248
	ds_read_b64_tr_b16 v[224:225], v198 offset:55552
	ds_read_b128 v[226:229], v200 offset:9216
	s_waitcnt lgkmcnt(8)
	v_mfma_f32_32x32x16_bf16 v[36:51], v[230:233], v[238:241], v[36:51]
	v_mfma_f32_32x32x16_bf16 v[4:19], v[242:245], v[238:241], v[4:19]
	s_waitcnt lgkmcnt(1)
	v_mfma_f32_32x32x16_bf16 v[52:67], v[218:221], v[222:225], v[52:67]
	s_waitcnt lgkmcnt(0)
	v_mfma_f32_32x32x16_bf16 v[20:35], v[226:229], v[222:225], v[20:35]
	ds_read_b64_tr_b16 v[224:225], v198 offset:55616
	ds_read_b64_tr_b16 v[222:223], v198 offset:53312
	s_waitcnt lgkmcnt(0)
	v_mfma_f32_32x32x16_bf16 v[36:51], v[218:221], v[222:225], v[36:51]
	v_mfma_f32_32x32x16_bf16 v[4:19], v[226:229], v[222:225], v[4:19]
	ds_read_b128 v[218:221], v201
	ds_read_b64_tr_b16 v[222:223], v198 offset:62464
	ds_read_b64_tr_b16 v[224:225], v198 offset:64768
	ds_read_b128 v[226:229], v201 offset:9216
	s_waitcnt lgkmcnt(1)
	v_mfma_f32_32x32x16_bf16 v[52:67], v[218:221], v[222:225], v[52:67]
	s_waitcnt lgkmcnt(0)
	v_mfma_f32_32x32x16_bf16 v[20:35], v[226:229], v[222:225], v[20:35]
	ds_read_b64_tr_b16 v[224:225], v198 offset:64832
	ds_read_b64_tr_b16 v[222:223], v198 offset:62528
	s_waitcnt lgkmcnt(0)
	v_mfma_f32_32x32x16_bf16 v[36:51], v[218:221], v[222:225], v[36:51]
	v_mfma_f32_32x32x16_bf16 v[4:19], v[226:229], v[222:225], v[4:19]
	s_cbranch_scc0 .LBB0_737
	s_lshl_b32 s36, s93, 6
	s_add_i32 s36, s36, 0x7fffd400
	s_and_b32 s36, s36, 0x7fffff00
	s_and_b32 s37, s92, 0x60
	s_or_b32 s36, s37, s36
	s_or_b32 s91, s36, 0x80
	s_mov_b64 s[36:37], 0
